# attention: long/short-first order now keyed on bx bit 3 so each XCD mixes both orders (on top of per-XCD head remap)
# baseline (speedup 1.0000x reference)
.LBB0_554:
	global_load_dword v7, v[2:3], off
	global_load_dword v8, v[4:5], off
	v_add_u32_e32 v6, 64, v6
	v_max_f32_e32 v1, v1, v1
	v_max_f32_e32 v0, v0, v0
	v_cmp_lt_u32_e32 vcc, s6, v6
	v_lshl_add_u64 v[2:3], v[2:3], 0, s[4:5]
	v_lshl_add_u64 v[4:5], v[4:5], 0, s[4:5]
	s_or_b64 s[2:3], vcc, s[2:3]
	s_waitcnt vmcnt(1)
	v_max_f32_e64 v7, |v7|, |v7|
	s_waitcnt vmcnt(0)
	v_max_f32_e64 v8, |v8|, |v8|
	v_max_f32_e32 v1, v1, v7
	v_max_f32_e32 v0, v0, v8
	s_andn2_b64 exec, exec, s[2:3]
	s_cbranch_execnz .LBB0_554
	s_or_b64 exec, exec, s[2:3]
	v_mbcnt_hi_u32_b32 v2, -1, v152
	v_and_b32_e32 v3, 64, v2
	v_add_u32_e32 v3, 64, v3
	v_xor_b32_e32 v4, 1, v2
	v_cmp_lt_i32_e32 vcc, v4, v3
	v_xor_b32_e32 v6, 2, v2
	v_xor_b32_e32 v7, 4, v2
	v_cndmask_b32_e32 v4, v2, v4, vcc
	v_lshlrev_b32_e32 v4, 2, v4
	ds_bpermute_b32 v5, v4, v1
	v_max_f32_e32 v1, v1, v1
	v_cmp_lt_i32_e32 vcc, v6, v3
	ds_bpermute_b32 v4, v4, v0
	v_max_f32_e32 v0, v0, v0
	s_waitcnt lgkmcnt(1)
	v_max_f32_e32 v5, v5, v5
	v_max_f32_e32 v1, v1, v5
	v_cndmask_b32_e32 v5, v2, v6, vcc
	v_lshlrev_b32_e32 v5, 2, v5
	ds_bpermute_b32 v6, v5, v1
	v_cmp_lt_i32_e32 vcc, v7, v3
	s_waitcnt lgkmcnt(1)
	v_max_f32_e32 v4, v4, v4
	v_max_f32_e32 v0, v0, v4
	ds_bpermute_b32 v4, v5, v0
	s_waitcnt lgkmcnt(1)
	v_max_f32_e32 v6, v6, v6
	v_max_f32_e32 v1, v1, v6
	v_cndmask_b32_e32 v6, v2, v7, vcc
	v_lshlrev_b32_e32 v6, 2, v6
	ds_bpermute_b32 v7, v6, v1
	v_xor_b32_e32 v8, 8, v2
	v_cmp_lt_i32_e32 vcc, v8, v3
	s_waitcnt lgkmcnt(1)
	v_max_f32_e32 v4, v4, v4
	v_max_f32_e32 v0, v0, v4
	s_waitcnt lgkmcnt(0)
	v_max_f32_e32 v7, v7, v7
	v_max_f32_e32 v1, v1, v7
	v_cndmask_b32_e32 v7, v2, v8, vcc
	v_lshlrev_b32_e32 v7, 2, v7
	ds_bpermute_b32 v8, v7, v1
	ds_bpermute_b32 v4, v6, v0
	v_writelane_b32 v246, s64, 38
	v_writelane_b32 v246, s88, 39
	s_waitcnt lgkmcnt(1)
	v_max_f32_e32 v5, v8, v8
	s_waitcnt lgkmcnt(0)
	v_max_f32_e32 v4, v4, v4
	v_max_f32_e32 v1, v1, v5
	v_xor_b32_e32 v5, 16, v2
	v_max_f32_e32 v0, v0, v4
	v_cmp_lt_i32_e32 vcc, v5, v3
	ds_bpermute_b32 v4, v7, v0
	v_writelane_b32 v246, s89, 40
	v_cndmask_b32_e32 v5, v2, v5, vcc
	v_lshlrev_b32_e32 v211, 2, v5
	v_writelane_b32 v246, s90, 41
	ds_bpermute_b32 v5, v211, v1
	v_writelane_b32 v246, s91, 42
	v_writelane_b32 v246, s65, 43
	s_waitcnt lgkmcnt(1)
	v_max_f32_e32 v4, v4, v4
	v_writelane_b32 v246, s66, 44
	v_max_f32_e32 v0, v0, v4
	ds_bpermute_b32 v4, v211, v0
	v_writelane_b32 v246, s67, 45
	v_writelane_b32 v246, s86, 46
	s_waitcnt lgkmcnt(1)
	v_max_f32_e32 v5, v5, v5
	v_max_f32_e32 v206, v1, v5
	v_writelane_b32 v246, s87, 47
	v_xor_b32_e32 v1, 32, v2
	v_writelane_b32 v246, s85, 48
	v_cmp_lt_i32_e32 vcc, v1, v3
	v_writelane_b32 v246, s70, 49
	s_nop 0
	v_cndmask_b32_e32 v1, v2, v1, vcc
	v_writelane_b32 v246, s71, 50
	v_lshlrev_b32_e32 v212, 2, v1
	s_waitcnt lgkmcnt(0)
	v_max_f32_e32 v1, v4, v4
	v_writelane_b32 v246, s80, 51
	v_max_f32_e32 v207, v0, v1
	ds_bpermute_b32 v208, v212, v206
	v_writelane_b32 v246, s81, 52
	ds_bpermute_b32 v209, v212, v207
	v_writelane_b32 v246, s92, 53
	v_mov_b32_e32 v0, v210
	s_bitcmp0_b32 s64, 3
	s_cselect_b64 s[94:95], -1, 0
	s_and_b64 vcc, exec, s[0:1]
	v_writelane_b32 v246, s93, 54
	v_writelane_b32 v246, s94, 55
	v_readfirstlane_b32 s2, v0
	s_ashr_i32 s68, s2, 6
	v_writelane_b32 v246, s95, 56
	s_mov_b64 s[2:3], -1
	v_writelane_b32 v246, s62, 57
	s_nop 1
	v_writelane_b32 v246, s63, 58
	s_cbranch_vccz .LBB0_625
	v_writelane_b32 v245, s82, 18
	s_add_i32 s0, s68, s82
	v_writelane_b32 v245, s68, 24
	s_cmpk_gt_i32 s0, 0x7ff
	v_writelane_b32 v245, s0, 20
	s_cbranch_scc1 .LBB0_568
	v_readlane_b32 s0, v245, 24
	s_mulk_i32 s0, 0x4100
	v_readlane_b32 s12, v246, 39
	s_add_i32 s2, s0, 0
	v_readlane_b32 s14, v246, 41
	v_readlane_b32 s15, v246, 42
	s_add_u32 s0, s14, 0x1a400000
	v_readlane_b32 s13, v246, 40
	v_writelane_b32 v246, s0, 62
	s_addc_u32 s0, s15, 0
	v_writelane_b32 v246, s0, 63
	s_mov_b32 s7, 0x20000
	v_readlane_b32 s0, v246, 36
	v_readlane_b32 s1, v246, 37
	s_brev_b32 s6, -2
	s_and_b32 s5, s1, 0xffff
	s_mov_b32 s4, s0
	s_and_b32 s13, s13, 0xffff
	v_mov_b32_e32 v173, 0
	v_mov_b32_e32 v213, s2
	v_mov_b32_e32 v214, 0xf300
	v_mov_b32_e32 v215, 0x14400
	v_mov_b32_e32 v216, 0x19500
	v_mov_b32_e32 v217, 0x1e600
	v_mov_b32_e32 v218, 0x358637bd
	v_readlane_b32 s3, v245, 20
	v_writelane_b32 v246, s2, 61
	s_branch .LBB0_559
